# chain row statistics: lane^16 / lane^32 butterfly by v_permlane16_swap / v_permlane32_swap instead of ds_bpermute round trips (on top of the specialised L stage)
# speedup vs baseline: 1.0040x; 1.0040x over previous
; #define LAS __attribute__((address_space(3)))
; #define MFMA16(a, b, c) __builtin_amdgcn_mfma_f32_16x16x32_bf16((a), (b), (c), 0, 0, 0)
; template <bool STORE> __device__ __forceinline__ void ret_chain(LAS unsigned char* lds, int b, int h, bf16* Qb, const bf16* Kb, const bf16* Vb, const bf16* Gb, const f32x2* tab, float* s_out) {
;     ...
; #pragma unroll
;             for (int ti = 0; ti < 4; ++ti)
; #pragma unroll
;                 for (int t = 0; t < 2; ++t) { if (32 * ks <= 64 * wr + 16 * ti + 15) acc_o[ti][t] = MFMA16(vf[t], pf[ti], acc_o[ti][t]);
;                     acc_s[ti][t] = MFMA16(ktf[ti], vf[t], acc_s[ti][t]); }
;         }
;         LAS f32x2* stats = (LAS f32x2*)(lds + RG4);
; #pragma unroll
;         for (int ti = 0; ti < 4; ++ti) {
;             float s = 0.f, q = 0.f;
; #pragma unroll
;             for (int t = 0; t < 2; ++t)
; #pragma unroll
;                 for (int r = 0; r < 4; ++r) { const float x = acc_o[ti][t][r]; s += x; q += x * x; }
;             s += __shfl_xor(s, 16); s += __shfl_xor(s, 32); q += __shfl_xor(q, 16); q += __shfl_xor(q, 32);
;             if (quad == 0) stats[(64 * wr + 16 * ti + l15) * 4 + wc] = (f32x2){s, q};
.LBB0_437:
	s_or_b64 exec, exec, vcc
	s_waitcnt lgkmcnt(0)
	v_mfma_f32_16x16x32_bf16 v[76:79], v[148:151], v[124:127], v[76:79]
	s_and_saveexec_b64 vcc, s[0:1]
	v_mfma_f32_16x16x32_bf16 v[104:107], v[128:131], v[144:147], v[104:107]
	s_or_b64 exec, exec, vcc
	v_mfma_f32_16x16x32_bf16 v[72:75], v[140:143], v[128:131], v[72:75]
	s_and_saveexec_b64 vcc, s[0:1]
	v_mfma_f32_16x16x32_bf16 v[100:103], v[124:127], v[144:147], v[100:103]
	s_or_b64 exec, exec, vcc
	v_mfma_f32_16x16x32_bf16 v[68:71], v[140:143], v[124:127], v[68:71]
	s_and_saveexec_b64 vcc, s[22:23]
	v_mfma_f32_16x16x32_bf16 v[96:99], v[128:131], v[136:139], v[96:99]
	s_or_b64 exec, exec, vcc
	v_mfma_f32_16x16x32_bf16 v[64:67], v[132:135], v[128:131], v[64:67]
	s_and_saveexec_b64 vcc, s[22:23]
	v_mfma_f32_16x16x32_bf16 v[92:95], v[124:127], v[136:139], v[92:95]
	s_or_b64 exec, exec, vcc
	v_mfma_f32_16x16x32_bf16 v[60:63], v[132:135], v[124:127], v[60:63]
	s_and_saveexec_b64 vcc, s[24:25]
	v_mfma_f32_16x16x32_bf16 v[88:91], v[128:131], v[120:123], v[88:91]
	s_or_b64 exec, exec, vcc
	v_mfma_f32_16x16x32_bf16 v[56:59], v[116:119], v[128:131], v[56:59]
	s_and_saveexec_b64 vcc, s[24:25]
	v_mfma_f32_16x16x32_bf16 v[84:87], v[124:127], v[120:123], v[84:87]
	s_or_b64 exec, exec, vcc
	v_mfma_f32_16x16x32_bf16 v[52:55], v[116:119], v[124:127], v[52:55]
	v_and_b32_e32 v117, 64, v208
	v_xor_b32_e32 v116, 16, v208
	v_add_u32_e32 v117, 64, v117
	v_cmp_lt_i32_e32 vcc, v116, v117
	v_pk_mul_f32 v[118:119], v[112:113], v[112:113]
	s_nop 0
	v_cndmask_b32_e32 v116, v208, v116, vcc
	v_lshlrev_b32_e32 v121, 2, v116
	v_xor_b32_e32 v116, 32, v208
	v_cmp_lt_i32_e32 vcc, v116, v117
	v_fmac_f32_e32 v119, v112, v112
	s_nop 0
	v_cndmask_b32_e32 v116, v208, v116, vcc
	v_lshlrev_b32_e32 v120, 2, v116
	v_add_f32_e32 v116, 0, v112
	v_add_f32_e32 v116, v113, v116
	v_add_f32_e32 v122, v114, v116
	v_pk_mul_f32 v[116:117], v[114:115], v[114:115]
	s_nop 0
	v_add_f32_e32 v118, v116, v119
	v_add_f32_e32 v116, v115, v122
	v_add_f32_e32 v119, v116, v108
	v_pk_mov_b32 v[116:117], v[114:115], v[108:109] op_sel:[1,0]
	v_pk_mul_f32 v[122:123], v[108:109], v[108:109]
	v_pk_mul_f32 v[116:117], v[116:117], v[116:117]
	s_nop 0
	v_add_f32_e32 v116, v116, v118
	v_add_f32_e32 v117, v116, v117
	v_add_f32_e32 v116, v109, v119
	v_pk_mul_f32 v[118:119], v[110:111], v[110:111]
	v_add_f32_e32 v117, v123, v117
	v_add_f32_e32 v116, v110, v116
	v_add_f32_e32 v119, v118, v117
	v_mul_f32_e32 v117, v111, v111
	v_mov_b32_e32 v118, v111
	v_pk_add_f32 v[116:117], v[118:119], v[116:117]
	v_mov_b32_e32 v118, v116
	v_mov_b32_e32 v119, v117
	s_nop 1
	v_permlane16_swap_b32_e32 v118, v116
	v_permlane16_swap_b32_e32 v119, v117
	v_pk_add_f32 v[116:117], v[116:117], v[118:119]
	v_mov_b32_e32 v118, v116
	v_mov_b32_e32 v119, v117
	s_nop 1
	v_permlane32_swap_b32_e32 v118, v116
	v_permlane32_swap_b32_e32 v119, v117
	s_and_saveexec_b64 vcc, s[26:27]
	s_cbranch_execz .LBB0_451
	s_waitcnt lgkmcnt(0)
	v_pk_add_f32 v[116:117], v[116:117], v[118:119]
	ds_write_b64 v206, v[116:117]
; template <bool STORE> __device__ __forceinline__ void ret_chain(LAS unsigned char* lds, int b, int h, bf16* Qb, const bf16* Kb, const bf16* Vb, const bf16* Gb, const f32x2* tab, float* s_out) {
;     ...
;         for (int ti = 0; ti < 4; ++ti) {
;             float s = 0.f, q = 0.f;
; #pragma unroll
;             for (int t = 0; t < 2; ++t)
; #pragma unroll
;                 for (int r = 0; r < 4; ++r) { const float x = acc_o[ti][t][r]; s += x; q += x * x; }
;             s += __shfl_xor(s, 16); s += __shfl_xor(s, 32); q += __shfl_xor(q, 16); q += __shfl_xor(q, 32);
;             if (quad == 0) stats[(64 * wr + 16 * ti + l15) * 4 + wc] = (f32x2){s, q};
;         }
.LBB0_451:
	s_or_b64 exec, exec, vcc
	v_add_f32_e32 v116, 0, v104
	v_add_f32_e32 v116, v105, v116
	s_waitcnt lgkmcnt(0)
	v_pk_mul_f32 v[118:119], v[104:105], v[104:105]
	v_add_f32_e32 v122, v106, v116
	v_pk_mul_f32 v[116:117], v[106:107], v[106:107]
	v_fmac_f32_e32 v119, v104, v104
	v_add_f32_e32 v118, v116, v119
	v_add_f32_e32 v116, v107, v122
	v_add_f32_e32 v119, v116, v100
	v_pk_mov_b32 v[116:117], v[106:107], v[100:101] op_sel:[1,0]
	v_pk_mul_f32 v[122:123], v[100:101], v[100:101]
	v_pk_mul_f32 v[116:117], v[116:117], v[116:117]
	s_nop 0
	v_add_f32_e32 v116, v116, v118
	v_add_f32_e32 v117, v116, v117
	v_add_f32_e32 v116, v101, v119
	v_pk_mul_f32 v[118:119], v[102:103], v[102:103]
	v_add_f32_e32 v117, v123, v117
	v_add_f32_e32 v116, v102, v116
	v_add_f32_e32 v119, v118, v117
	v_mul_f32_e32 v117, v103, v103
	v_mov_b32_e32 v118, v103
	v_pk_add_f32 v[116:117], v[118:119], v[116:117]
	v_mov_b32_e32 v118, v116
	v_mov_b32_e32 v119, v117
	s_nop 1
	v_permlane16_swap_b32_e32 v118, v116
	v_permlane16_swap_b32_e32 v119, v117
	v_pk_add_f32 v[116:117], v[116:117], v[118:119]
	v_mov_b32_e32 v118, v116
	v_mov_b32_e32 v119, v117
	s_nop 1
	v_permlane32_swap_b32_e32 v118, v116
	v_permlane32_swap_b32_e32 v119, v117
	s_and_saveexec_b64 vcc, s[26:27]
	s_cbranch_execz .LBB0_453
	s_waitcnt lgkmcnt(0)
	v_pk_add_f32 v[116:117], v[116:117], v[118:119]
	ds_write_b64 v206, v[116:117] offset:512
.LBB0_453:
	s_or_b64 exec, exec, vcc
	v_add_f32_e32 v116, 0, v96
	v_add_f32_e32 v116, v97, v116
	s_waitcnt lgkmcnt(0)
	v_pk_mul_f32 v[118:119], v[96:97], v[96:97]
	v_add_f32_e32 v122, v98, v116
	v_pk_mul_f32 v[116:117], v[98:99], v[98:99]
	v_fmac_f32_e32 v119, v96, v96
	v_add_f32_e32 v118, v116, v119
	v_add_f32_e32 v116, v99, v122
	v_add_f32_e32 v119, v116, v92
	v_pk_mov_b32 v[116:117], v[98:99], v[92:93] op_sel:[1,0]
	v_pk_mul_f32 v[122:123], v[92:93], v[92:93]
	v_pk_mul_f32 v[116:117], v[116:117], v[116:117]
	s_nop 0
	v_add_f32_e32 v116, v116, v118
	v_add_f32_e32 v117, v116, v117
	v_add_f32_e32 v116, v93, v119
	v_pk_mul_f32 v[118:119], v[94:95], v[94:95]
	v_add_f32_e32 v117, v123, v117
	v_add_f32_e32 v116, v94, v116
	v_add_f32_e32 v119, v118, v117
	v_mul_f32_e32 v117, v95, v95
	v_mov_b32_e32 v118, v95
	v_pk_add_f32 v[116:117], v[118:119], v[116:117]
	v_mov_b32_e32 v118, v116
	v_mov_b32_e32 v119, v117
	s_nop 1
	v_permlane16_swap_b32_e32 v118, v116
	v_permlane16_swap_b32_e32 v119, v117
	v_pk_add_f32 v[116:117], v[116:117], v[118:119]
	v_mov_b32_e32 v118, v116
	v_mov_b32_e32 v119, v117
	s_nop 1
	v_permlane32_swap_b32_e32 v118, v116
	v_permlane32_swap_b32_e32 v119, v117
	s_and_saveexec_b64 vcc, s[26:27]
	s_cbranch_execz .LBB0_455
	s_waitcnt lgkmcnt(0)
	v_pk_add_f32 v[116:117], v[116:117], v[118:119]
	ds_write_b64 v206, v[116:117] offset:1024
.LBB0_455:
	s_or_b64 exec, exec, vcc
	v_add_f32_e32 v116, 0, v88
	v_add_f32_e32 v116, v89, v116
	s_waitcnt lgkmcnt(0)
	v_pk_mul_f32 v[118:119], v[88:89], v[88:89]
	v_add_f32_e32 v122, v90, v116
	v_pk_mul_f32 v[116:117], v[90:91], v[90:91]
	v_fmac_f32_e32 v119, v88, v88
	v_add_f32_e32 v118, v116, v119
	v_add_f32_e32 v116, v91, v122
	v_add_f32_e32 v119, v116, v84
	v_pk_mov_b32 v[116:117], v[90:91], v[84:85] op_sel:[1,0]
	v_pk_mul_f32 v[122:123], v[84:85], v[84:85]
	v_pk_mul_f32 v[116:117], v[116:117], v[116:117]
	s_nop 0
	v_add_f32_e32 v116, v116, v118
	v_add_f32_e32 v117, v116, v117
	v_add_f32_e32 v116, v85, v119
	v_pk_mul_f32 v[118:119], v[86:87], v[86:87]
	v_add_f32_e32 v117, v123, v117
	v_add_f32_e32 v116, v86, v116
	v_add_f32_e32 v119, v118, v117
	v_mul_f32_e32 v117, v87, v87
	v_mov_b32_e32 v118, v87
	v_pk_add_f32 v[116:117], v[118:119], v[116:117]
	v_mov_b32_e32 v118, v116
	v_mov_b32_e32 v119, v117
	s_nop 1
	v_permlane16_swap_b32_e32 v118, v116
	v_permlane16_swap_b32_e32 v119, v117
	v_pk_add_f32 v[116:117], v[116:117], v[118:119]
	v_mov_b32_e32 v118, v116
	v_mov_b32_e32 v119, v117
	s_nop 1
	v_permlane32_swap_b32_e32 v118, v116
	v_permlane32_swap_b32_e32 v119, v117
	s_and_saveexec_b64 vcc, s[26:27]
	s_cbranch_execz .LBB0_457
	s_waitcnt lgkmcnt(0)
	v_pk_add_f32 v[116:117], v[116:117], v[118:119]
	ds_write_b64 v206, v[116:117] offset:1536
